# conformer conv tap loop: 32 v_fmac_f32 per tap with fixed accumulators instead of 16 v_pk_fma_f32 + ~22 register-rotation v_mov per tap
# baseline (speedup 1.0000x reference)
; #define LAS __attribute__((address_space(3)))
; __device__ void conv_unit(LAS unsigned char* lds, const bf16_t* __restrict__ Z, bf16_t* __restrict__ MIX, int unit,
;                           const float* __restrict__ ccw, const float* __restrict__ ccb, const float* __restrict__ lng, const float* __restrict__ lnb, const float* __restrict__ scw) {
;     ...
;     { const int ch = tid & 255, half = tid >> 8; float acc[32]; const float bias = ccb[ch];
; #pragma unroll
;       for (int j = 0; j < 32; ++j) acc[j] = bias;
;       for (int k = 0; k < 31; ++k) { const float w = ccw[k * 256 + ch]; LAS const float* up = ub + (half * 32 + k) * 256 + ch;
; #pragma unroll
;           for (int j = 0; j < 32; ++j) acc[j] = __builtin_fmaf(w, up[j * 256], acc[j]); }
.LBB0_139:
	s_or_b64 exec, exec, s[10:11]
	v_lshlrev_b32_e32 v102, 2, v100
	s_waitcnt vmcnt(1)
	v_and_b32_e32 v2, 0x3fc, v102
	s_waitcnt lgkmcnt(0)
	s_barrier
	global_load_dword v68, v2, s[0:1]
	v_lshlrev_b32_e32 v4, 7, v100
	v_mov_b32_e32 v3, v1
	v_and_b32_e32 v4, 0xffff8000, v4
	s_mov_b32 s3, 0
	v_add3_u32 v103, 0, v4, v2
	v_add_u32_e32 v2, 0x18000, v2
	s_waitcnt vmcnt(0)
	v_mov_b32_e32 v4, v68
	v_mov_b32_e32 v5, v68
	v_mov_b32_e32 v6, v68
	v_mov_b32_e32 v7, v68
	v_mov_b32_e32 v8, v68
	v_mov_b32_e32 v9, v68
	v_mov_b32_e32 v10, v68
	v_mov_b32_e32 v11, v68
	v_mov_b32_e32 v12, v68
	v_mov_b32_e32 v13, v68
	v_mov_b32_e32 v14, v68
	v_mov_b32_e32 v15, v68
	v_mov_b32_e32 v16, v68
	v_mov_b32_e32 v17, v68
	v_mov_b32_e32 v18, v68
	v_mov_b32_e32 v19, v68
	v_mov_b32_e32 v20, v68
	v_mov_b32_e32 v21, v68
	v_mov_b32_e32 v22, v68
	v_mov_b32_e32 v23, v68
	v_mov_b32_e32 v24, v68
	v_mov_b32_e32 v25, v68
	v_mov_b32_e32 v26, v68
	v_mov_b32_e32 v27, v68
	v_mov_b32_e32 v28, v68
	v_mov_b32_e32 v29, v68
	v_mov_b32_e32 v30, v68
	v_mov_b32_e32 v31, v68
	v_mov_b32_e32 v32, v68
	v_mov_b32_e32 v33, v68
	v_mov_b32_e32 v34, v68
	v_mov_b32_e32 v35, v68
.LBB0_141:
	v_add_u32_e32 v3, s3, v2
	v_add_u32_e32 v104, s3, v103
	ds_read_b32 v70, v3
	ds_read_b32 v71, v3 offset:1024
	ds_read2st64_b32 v[36:37], v104 offset1:4
	ds_read2st64_b32 v[38:39], v104 offset0:8 offset1:12
	ds_read2st64_b32 v[40:41], v104 offset0:16 offset1:20
	ds_read2st64_b32 v[42:43], v104 offset0:24 offset1:28
	ds_read2st64_b32 v[44:45], v104 offset0:32 offset1:36
	ds_read2st64_b32 v[46:47], v104 offset0:40 offset1:44
	ds_read2st64_b32 v[48:49], v104 offset0:48 offset1:52
	ds_read2st64_b32 v[50:51], v104 offset0:56 offset1:60
	ds_read2st64_b32 v[52:53], v104 offset0:64 offset1:68
	ds_read2st64_b32 v[54:55], v104 offset0:72 offset1:76
	ds_read2st64_b32 v[56:57], v104 offset0:80 offset1:84
	ds_read2st64_b32 v[58:59], v104 offset0:88 offset1:92
	ds_read2st64_b32 v[60:61], v104 offset0:96 offset1:100
	ds_read2st64_b32 v[62:63], v104 offset0:104 offset1:108
	ds_read2st64_b32 v[64:65], v104 offset0:112 offset1:116
	ds_read2st64_b32 v[66:67], v104 offset0:120 offset1:124
	ds_read_b32 v105, v104 offset:32768
	s_waitcnt lgkmcnt(15)
	v_fmac_f32_e32 v4, v70, v36
	v_fmac_f32_e32 v5, v70, v37
	s_waitcnt lgkmcnt(15)
	v_fmac_f32_e32 v6, v70, v38
	v_fmac_f32_e32 v7, v70, v39
	s_waitcnt lgkmcnt(14)
	v_fmac_f32_e32 v8, v70, v40
	v_fmac_f32_e32 v9, v70, v41
	s_waitcnt lgkmcnt(13)
	v_fmac_f32_e32 v10, v70, v42
	v_fmac_f32_e32 v11, v70, v43
	s_waitcnt lgkmcnt(12)
	v_fmac_f32_e32 v12, v70, v44
	v_fmac_f32_e32 v13, v70, v45
	s_waitcnt lgkmcnt(11)
	v_fmac_f32_e32 v14, v70, v46
	v_fmac_f32_e32 v15, v70, v47
	s_waitcnt lgkmcnt(10)
	v_fmac_f32_e32 v16, v70, v48
	v_fmac_f32_e32 v17, v70, v49
	s_waitcnt lgkmcnt(9)
	v_fmac_f32_e32 v18, v70, v50
	v_fmac_f32_e32 v19, v70, v51
	s_waitcnt lgkmcnt(8)
	v_fmac_f32_e32 v20, v70, v52
	v_fmac_f32_e32 v21, v70, v53
	s_waitcnt lgkmcnt(7)
	v_fmac_f32_e32 v22, v70, v54
	v_fmac_f32_e32 v23, v70, v55
	s_waitcnt lgkmcnt(6)
	v_fmac_f32_e32 v24, v70, v56
	v_fmac_f32_e32 v25, v70, v57
	s_waitcnt lgkmcnt(5)
	v_fmac_f32_e32 v26, v70, v58
	v_fmac_f32_e32 v27, v70, v59
	s_waitcnt lgkmcnt(4)
	v_fmac_f32_e32 v28, v70, v60
	v_fmac_f32_e32 v29, v70, v61
	s_waitcnt lgkmcnt(3)
	v_fmac_f32_e32 v30, v70, v62
	v_fmac_f32_e32 v31, v70, v63
	s_waitcnt lgkmcnt(2)
	v_fmac_f32_e32 v32, v70, v64
	v_fmac_f32_e32 v33, v70, v65
	s_waitcnt lgkmcnt(1)
	v_fmac_f32_e32 v34, v70, v66
	v_fmac_f32_e32 v35, v70, v67
	s_cmpk_eq_i32 s3, 0x7800
	s_cbranch_scc1 .Lcv_taps_done
	v_fmac_f32_e32 v4, v71, v37
	v_fmac_f32_e32 v5, v71, v38
	v_fmac_f32_e32 v6, v71, v39
	v_fmac_f32_e32 v7, v71, v40
	v_fmac_f32_e32 v8, v71, v41
	v_fmac_f32_e32 v9, v71, v42
	v_fmac_f32_e32 v10, v71, v43
	v_fmac_f32_e32 v11, v71, v44
	v_fmac_f32_e32 v12, v71, v45
	v_fmac_f32_e32 v13, v71, v46
	v_fmac_f32_e32 v14, v71, v47
	v_fmac_f32_e32 v15, v71, v48
	v_fmac_f32_e32 v16, v71, v49
	v_fmac_f32_e32 v17, v71, v50
	v_fmac_f32_e32 v18, v71, v51
	v_fmac_f32_e32 v19, v71, v52
	v_fmac_f32_e32 v20, v71, v53
	v_fmac_f32_e32 v21, v71, v54
	v_fmac_f32_e32 v22, v71, v55
	v_fmac_f32_e32 v23, v71, v56
	v_fmac_f32_e32 v24, v71, v57
	v_fmac_f32_e32 v25, v71, v58
	v_fmac_f32_e32 v26, v71, v59
	v_fmac_f32_e32 v27, v71, v60
	v_fmac_f32_e32 v28, v71, v61
	v_fmac_f32_e32 v29, v71, v62
	v_fmac_f32_e32 v30, v71, v63
	v_fmac_f32_e32 v31, v71, v64
	v_fmac_f32_e32 v32, v71, v65
	v_fmac_f32_e32 v33, v71, v66
	v_fmac_f32_e32 v34, v71, v67
	s_waitcnt lgkmcnt(0)
	v_fmac_f32_e32 v35, v71, v105
	s_addk_i32 s3, 0x800
	s_branch .LBB0_141

; #define LAS __attribute__((address_space(3)))
; __device__ __forceinline__ unsigned cvtpk(float lo, float hi) { f32x2_t v = {lo, hi}; bf16x2_t b = __builtin_convertvector(v, bf16x2_t); return __builtin_bit_cast(unsigned, b); }
; __device__ __forceinline__ float wave_sum(float v) { v += __shfl_xor(v, 32); v += __shfl_xor(v, 16); v += __shfl_xor(v, 8); v += __shfl_xor(v, 4); v += __shfl_xor(v, 2); v += __shfl_xor(v, 1); return v; }
; __device__ __forceinline__ float silu_f(float g) { return g * __builtin_amdgcn_rcpf(1.f + __builtin_amdgcn_exp2f(g * -1.4426950408889634f)); }
; __device__ void conv_unit(LAS unsigned char* lds, const bf16_t* __restrict__ Z, bf16_t* __restrict__ MIX, int unit,
;                           const float* __restrict__ ccw, const float* __restrict__ ccb, const float* __restrict__ lng, const float* __restrict__ lnb, const float* __restrict__ scw) {
;     ...
;       __syncthreads();
; #pragma unroll
;       for (int j = 0; j < 32; ++j) ub[(half * 32 + j) * 256 + ch] = acc[j]; }
;     __syncthreads();
;     { const int wid = tid >> 6, lane = tid & 63; const f32x4 gg = *(const f32x4*)(lng + lane * 4), bb = *(const f32x4*)(lnb + lane * 4);
;       for (int j = 0; j < 8; ++j) { const int tok = wid * 8 + j; const f32x4 y = *(LAS const f32x4*)(ub + tok * 256 + lane * 4);
;           const float mean = wave_sum(y[0] + y[1] + y[2] + y[3]) * (1.f / 256.f); const f32x4 d = y - mean;
;           const float var = wave_sum(d[0] * d[0] + d[1] * d[1] + d[2] * d[2] + d[3] * d[3]) * (1.f / 256.f), rstd = rsqrtf(var + 1e-6f);
;           const f32x4 z = d * rstd * gg + bb; u32x2 w; w.x = cvtpk(silu_f(z[0]), silu_f(z[1])); w.y = cvtpk(silu_f(z[2]), silu_f(z[3]));
;           *(u32x2*)(MIX + (size_t)(t0 + tok) * DM + 512 + lane * 4) = w; } }
.LBB0_143:
	s_barrier
	ds_write2st64_b32 v103, v4, v5 offset1:4
	ds_write2st64_b32 v103, v6, v7 offset0:8 offset1:12
	ds_write2st64_b32 v103, v8, v9 offset0:16 offset1:20
	ds_write2st64_b32 v103, v10, v11 offset0:24 offset1:28
	ds_write2st64_b32 v103, v12, v13 offset0:32 offset1:36
	ds_write2st64_b32 v103, v14, v15 offset0:40 offset1:44
	ds_write2st64_b32 v103, v16, v17 offset0:48 offset1:52
	ds_write2st64_b32 v103, v18, v19 offset0:56 offset1:60
	ds_write2st64_b32 v103, v20, v21 offset0:64 offset1:68
	ds_write2st64_b32 v103, v22, v23 offset0:72 offset1:76
	ds_write2st64_b32 v103, v24, v25 offset0:80 offset1:84
	ds_write2st64_b32 v103, v26, v27 offset0:88 offset1:92
	ds_write2st64_b32 v103, v28, v29 offset0:96 offset1:100
	ds_write2st64_b32 v103, v30, v31 offset0:104 offset1:108
	ds_write2st64_b32 v103, v32, v33 offset0:112 offset1:116
	ds_write2st64_b32 v103, v34, v35 offset0:120 offset1:124
	v_and_b32_e32 v25, 0xfc, v102
	v_lshlrev_b32_e32 v6, 2, v25
	v_ashrrev_i32_e32 v22, 3, v100
	v_and_b32_e32 v24, -8, v22
	v_add_u32_e32 v23, 0, v6
	v_lshl_add_u32 v2, v24, 10, v23
	s_waitcnt lgkmcnt(0)
	s_barrier
	ds_read_b128 v[26:29], v2
	v_or_b32_e32 v44, 1, v24
	v_lshl_add_u32 v2, v44, 10, v23
	ds_read_b128 v[12:15], v2
	s_mov_b32 s10, 0x358637bd
	s_waitcnt lgkmcnt(1)
	v_add_f32_e32 v2, v26, v27
	v_add_f32_e32 v2, v28, v2
	v_add_f32_e32 v2, v29, v2
	ds_bpermute_b32 v3, v170, v2
	s_waitcnt lgkmcnt(1)
	v_add_f32_e32 v4, v12, v13
	v_add_f32_e32 v4, v14, v4
	v_add_f32_e32 v4, v15, v4
	ds_bpermute_b32 v5, v170, v4
	s_waitcnt lgkmcnt(1)
	v_add_f32_e32 v2, v2, v3
	ds_bpermute_b32 v3, v171, v2
	v_readlane_b32 s14, v252, 18
	v_readlane_b32 s15, v252, 19
	s_waitcnt lgkmcnt(1)
	v_add_f32_e32 v4, v4, v5
	ds_bpermute_b32 v5, v171, v4
	s_waitcnt lgkmcnt(1)
	v_add_f32_e32 v2, v2, v3
	ds_bpermute_b32 v3, v172, v2
	v_or_b32_e32 v45, 3, v24
	v_readlane_b32 s20, v252, 20
	s_waitcnt lgkmcnt(1)
	v_add_f32_e32 v4, v4, v5
	ds_bpermute_b32 v5, v172, v4
	s_waitcnt lgkmcnt(1)
	v_add_f32_e32 v2, v2, v3
	ds_bpermute_b32 v3, v173, v2
	v_readlane_b32 s21, v252, 21
	s_waitcnt lgkmcnt(1)
	v_add_f32_e32 v4, v4, v5
	ds_bpermute_b32 v5, v173, v4
	s_waitcnt lgkmcnt(1)
	v_add_f32_e32 v2, v2, v3
	ds_bpermute_b32 v3, v174, v2
	s_waitcnt lgkmcnt(1)
	v_add_f32_e32 v16, v4, v5
	ds_bpermute_b32 v17, v174, v16
	s_waitcnt lgkmcnt(1)
	v_add_f32_e32 v10, v2, v3
	global_load_dwordx4 v[2:5], v6, s[36:37]
	s_nop 0
	global_load_dwordx4 v[6:9], v6, s[38:39]
	ds_bpermute_b32 v11, v175, v10
	s_waitcnt lgkmcnt(1)
	v_add_f32_e32 v20, v16, v17
	ds_bpermute_b32 v21, v175, v20
	s_waitcnt lgkmcnt(1)
	v_add_f32_e32 v18, v10, v11
	v_fmamk_f32 v11, v18, 0xbb800000, v27
	v_fmamk_f32 v10, v18, 0xbb800000, v26
	s_waitcnt lgkmcnt(0)
	v_add_f32_e32 v20, v20, v21
	v_fmamk_f32 v31, v20, 0xbb800000, v13
	v_fmamk_f32 v30, v20, 0xbb800000, v12
	v_fmamk_f32 v29, v18, 0xbb800000, v29
	v_fmac_f32_e32 v28, 0xbb800000, v18
	v_pk_mul_f32 v[18:19], v[10:11], v[10:11]
	v_fmamk_f32 v15, v20, 0xbb800000, v15
	v_fmac_f32_e32 v14, 0xbb800000, v20
	v_pk_mul_f32 v[20:21], v[30:31], v[30:31]
	v_pk_mul_f32 v[16:17], v[28:29], v[28:29]
	v_pk_mul_f32 v[12:13], v[14:15], v[14:15]
	v_mov_b32_e32 v26, v20
	v_mov_b32_e32 v27, v18
	v_mov_b32_e32 v18, v21
	v_pk_add_f32 v[18:19], v[26:27], v[18:19]
	v_mov_b32_e32 v20, v12
	v_mov_b32_e32 v21, v16
	v_pk_add_f32 v[18:19], v[20:21], v[18:19]
	v_mov_b32_e32 v16, v13
	v_pk_add_f32 v[12:13], v[16:17], v[18:19]
	ds_bpermute_b32 v17, v170, v13
	ds_bpermute_b32 v16, v170, v12
	v_mov_b64_e32 v[20:21], s[10:11]
	s_mov_b32 s10, 0x3b800000
	v_add_u32_e32 v18, s17, v24
	v_ashrrev_i32_e32 v19, 31, v18
	s_waitcnt lgkmcnt(0)
	v_pk_add_f32 v[12:13], v[12:13], v[16:17]
	ds_bpermute_b32 v17, v171, v13
	ds_bpermute_b32 v16, v171, v12
	v_lshlrev_b64 v[18:19], 11, v[18:19]
	v_lshl_add_u64 v[26:27], s[14:15], 0, v[18:19]
	v_lshlrev_b32_e32 v18, 1, v25
	v_mov_b32_e32 v19, v1
	s_waitcnt lgkmcnt(0)
	v_pk_add_f32 v[12:13], v[12:13], v[16:17]
	ds_bpermute_b32 v17, v172, v13
	ds_bpermute_b32 v16, v172, v12
	s_waitcnt lgkmcnt(0)
	v_pk_add_f32 v[12:13], v[12:13], v[16:17]
	ds_bpermute_b32 v17, v173, v13
	ds_bpermute_b32 v16, v173, v12
	s_waitcnt lgkmcnt(0)
	v_pk_add_f32 v[12:13], v[12:13], v[16:17]
	ds_bpermute_b32 v17, v174, v13
	ds_bpermute_b32 v16, v174, v12
	s_waitcnt lgkmcnt(0)
	v_pk_add_f32 v[12:13], v[12:13], v[16:17]
	ds_bpermute_b32 v17, v175, v13
	ds_bpermute_b32 v16, v175, v12
	s_waitcnt lgkmcnt(0)
	v_pk_add_f32 v[12:13], v[12:13], v[16:17]
	s_nop 0
	v_pk_fma_f32 v[12:13], v[12:13], s[10:11], v[20:21] op_sel_hi:[1,0,0]
	s_nop 0
	v_mul_f32_e32 v16, 0x4b800000, v13
	v_cmp_gt_f32_e32 vcc, s27, v13
	s_nop 1
	v_cndmask_b32_e32 v13, v13, v16, vcc
	v_rsq_f32_e32 v13, v13
	v_lshl_add_u64 v[16:17], v[26:27], 0, v[18:19]
	v_mul_f32_e32 v25, 0x45800000, v13
	v_cndmask_b32_e32 v26, v13, v25, vcc
	v_pk_mul_f32 v[10:11], v[10:11], v[26:27] op_sel_hi:[1,0]
	v_pk_mul_f32 v[26:27], v[28:29], v[26:27] op_sel_hi:[1,0]
	s_waitcnt vmcnt(0)
	v_pk_fma_f32 v[10:11], v[2:3], v[10:11], v[6:7]
	v_pk_fma_f32 v[32:33], v[4:5], v[26:27], v[8:9]
	v_mul_f32_e32 v13, 0xbfb8aa3b, v10
	v_exp_f32_e32 v13, v13
	v_mul_f32_e32 v25, 0xbfb8aa3b, v11
	v_exp_f32_e32 v25, v25
	v_cmp_gt_f32_e32 vcc, s27, v12
	v_add_f32_e32 v13, 1.0, v13
	v_rcp_f32_e32 v26, v13
	v_add_f32_e32 v13, 1.0, v25
	v_rcp_f32_e32 v27, v13
	v_mul_f32_e32 v13, 0xbfb8aa3b, v32
	v_exp_f32_e32 v13, v13
	v_mul_f32_e32 v25, 0xbfb8aa3b, v33
	v_exp_f32_e32 v25, v25
	v_pk_mul_f32 v[34:35], v[10:11], v[26:27]
	v_add_f32_e32 v10, 1.0, v13
	v_rcp_f32_e32 v36, v10
	v_add_f32_e32 v10, 1.0, v25
	v_or_b32_e32 v25, 2, v24
	v_lshl_add_u32 v11, v25, 10, v23
	ds_read_b128 v[26:29], v11
	v_rcp_f32_e32 v37, v10
	v_mul_f32_e32 v10, 0x4b800000, v12
	v_cndmask_b32_e32 v10, v12, v10, vcc
	v_rsq_f32_e32 v38, v10
	v_lshl_add_u32 v10, v45, 10, v23
	s_waitcnt lgkmcnt(0)
; #define LAS __attribute__((address_space(3)))
; __device__ __forceinline__ unsigned cvtpk(float lo, float hi) { f32x2_t v = {lo, hi}; bf16x2_t b = __builtin_convertvector(v, bf16x2_t); return __builtin_bit_cast(unsigned, b); }
; __device__ __forceinline__ float wave_sum(float v) { v += __shfl_xor(v, 32); v += __shfl_xor(v, 16); v += __shfl_xor(v, 8); v += __shfl_xor(v, 4); v += __shfl_xor(v, 2); v += __shfl_xor(v, 1); return v; }
; __device__ __forceinline__ float silu_f(float g) { return g * __builtin_amdgcn_rcpf(1.f + __builtin_amdgcn_exp2f(g * -1.4426950408889634f)); }
; __device__ void conv_unit(LAS unsigned char* lds, const bf16_t* __restrict__ Z, bf16_t* __restrict__ MIX, int unit,
;                           const float* __restrict__ ccw, const float* __restrict__ ccb, const float* __restrict__ lng, const float* __restrict__ lnb, const float* __restrict__ scw) {
;     ...
;     { const int wid = tid >> 6, lane = tid & 63; const f32x4 gg = *(const f32x4*)(lng + lane * 4), bb = *(const f32x4*)(lnb + lane * 4);
;       for (int j = 0; j < 8; ++j) { const int tok = wid * 8 + j; const f32x4 y = *(LAS const f32x4*)(ub + tok * 256 + lane * 4);
;           const float mean = wave_sum(y[0] + y[1] + y[2] + y[3]) * (1.f / 256.f); const f32x4 d = y - mean;
;           const float var = wave_sum(d[0] * d[0] + d[1] * d[1] + d[2] * d[2] + d[3] * d[3]) * (1.f / 256.f), rstd = rsqrtf(var + 1e-6f);
;           const f32x4 z = d * rstd * gg + bb; u32x2 w; w.x = cvtpk(silu_f(z[0]), silu_f(z[1])); w.y = cvtpk(silu_f(z[2]), silu_f(z[3]));
;           *(u32x2*)(MIX + (size_t)(t0 + tok) * DM + 512 + lane * 4) = w; } }
	v_add_f32_e32 v39, v26, v27
	ds_read_b128 v[10:13], v10
	v_add_f32_e32 v39, v28, v39
	v_add_f32_e32 v39, v29, v39
	ds_bpermute_b32 v40, v170, v39
	v_pk_mul_f32 v[32:33], v[32:33], v[36:37]
	s_waitcnt lgkmcnt(1)
	v_add_f32_e32 v37, v10, v11
	v_add_f32_e32 v37, v12, v37
	v_cvt_pk_bf16_f32 v34, v34, v35
	v_cvt_pk_bf16_f32 v35, v32, v33
	s_waitcnt lgkmcnt(0)
	v_add_f32_e32 v33, v39, v40
	v_add_f32_e32 v37, v13, v37
	ds_bpermute_b32 v36, v171, v33
	ds_bpermute_b32 v39, v170, v37
	v_mul_f32_e32 v32, 0x45800000, v38
	v_cndmask_b32_e32 v32, v38, v32, vcc
	global_store_dwordx2 v[16:17], v[34:35], off offset:1024
	s_waitcnt lgkmcnt(1)
	v_add_f32_e32 v33, v33, v36
	s_waitcnt lgkmcnt(0)
	v_add_f32_e32 v37, v37, v39
	ds_bpermute_b32 v36, v172, v33
	ds_bpermute_b32 v38, v171, v37
	v_pk_mul_f32 v[30:31], v[30:31], v[32:33] op_sel_hi:[1,0]
	v_pk_mul_f32 v[14:15], v[14:15], v[32:33] op_sel_hi:[1,0]
	v_pk_fma_f32 v[30:31], v[2:3], v[30:31], v[6:7]
	s_waitcnt lgkmcnt(1)
	v_add_f32_e32 v32, v33, v36
	s_waitcnt lgkmcnt(0)
	v_add_f32_e32 v36, v37, v38
	ds_bpermute_b32 v37, v172, v36
	ds_bpermute_b32 v33, v173, v32
	v_mul_f32_e32 v38, 0xbfb8aa3b, v30
	v_exp_f32_e32 v46, v38
	v_mul_f32_e32 v38, 0xbfb8aa3b, v31
	s_waitcnt lgkmcnt(1)
	v_add_f32_e32 v36, v36, v37
	ds_bpermute_b32 v37, v173, v36
	s_waitcnt lgkmcnt(1)
	v_add_f32_e32 v32, v32, v33
	ds_bpermute_b32 v33, v174, v32
	v_exp_f32_e32 v47, v38
	v_pk_fma_f32 v[14:15], v[4:5], v[14:15], v[8:9]
	s_waitcnt lgkmcnt(1)
	v_add_f32_e32 v36, v36, v37
	ds_bpermute_b32 v37, v174, v36
	s_waitcnt lgkmcnt(1)
	v_add_f32_e32 v32, v32, v33
	ds_bpermute_b32 v33, v175, v32
	s_waitcnt lgkmcnt(1)
	v_add_f32_e32 v38, v36, v37
	ds_bpermute_b32 v39, v175, v38
	s_waitcnt lgkmcnt(1)
	v_add_f32_e32 v32, v32, v33
	v_fmamk_f32 v27, v32, 0xbb800000, v27
	v_fmamk_f32 v26, v32, 0xbb800000, v26
	v_fmamk_f32 v29, v32, 0xbb800000, v29
	s_waitcnt lgkmcnt(0)
	v_add_f32_e32 v38, v38, v39
	v_fmamk_f32 v11, v38, 0xbb800000, v11
	v_fmamk_f32 v10, v38, 0xbb800000, v10
	v_fmac_f32_e32 v28, 0xbb800000, v32
	v_pk_mul_f32 v[36:37], v[26:27], v[26:27]
	v_fmamk_f32 v13, v38, 0xbb800000, v13
	v_fmac_f32_e32 v12, 0xbb800000, v38
	v_pk_mul_f32 v[40:41], v[10:11], v[10:11]
	v_pk_mul_f32 v[32:33], v[28:29], v[28:29]
	v_pk_mul_f32 v[38:39], v[12:13], v[12:13]
	v_mov_b32_e32 v42, v40
	v_mov_b32_e32 v43, v36
	v_mov_b32_e32 v36, v41
	v_pk_add_f32 v[36:37], v[42:43], v[36:37]
	v_mov_b32_e32 v40, v38
	v_mov_b32_e32 v41, v32
	v_pk_add_f32 v[36:37], v[40:41], v[36:37]
	v_mov_b32_e32 v32, v39
	v_pk_add_f32 v[32:33], v[32:33], v[36:37]
	ds_bpermute_b32 v37, v170, v33
	ds_bpermute_b32 v36, v170, v32
	v_add_f32_e32 v38, 1.0, v46
	v_add_f32_e32 v39, 1.0, v47
	v_rcp_f32_e32 v38, v38
	v_rcp_f32_e32 v39, v39
	s_waitcnt lgkmcnt(0)
	v_pk_add_f32 v[32:33], v[32:33], v[36:37]
	ds_bpermute_b32 v37, v171, v33
	ds_bpermute_b32 v36, v171, v32
	v_mul_f32_e32 v40, 0xbfb8aa3b, v14
	v_mul_f32_e32 v41, 0xbfb8aa3b, v15
	v_exp_f32_e32 v40, v40
	v_exp_f32_e32 v41, v41
	s_waitcnt lgkmcnt(0)
	v_pk_add_f32 v[32:33], v[32:33], v[36:37]
	ds_bpermute_b32 v37, v172, v33
	ds_bpermute_b32 v36, v172, v32
	v_pk_mul_f32 v[16:17], v[30:31], v[38:39]
	v_add_f32_e32 v40, 1.0, v40
	v_add_f32_e32 v41, 1.0, v41
	v_rcp_f32_e32 v40, v40
	s_waitcnt lgkmcnt(0)
	v_pk_add_f32 v[32:33], v[32:33], v[36:37]
	ds_bpermute_b32 v37, v173, v33
	ds_bpermute_b32 v36, v173, v32
	v_rcp_f32_e32 v41, v41
	v_cvt_pk_bf16_f32 v16, v16, v17
	v_or_b32_e32 v42, 5, v24
	s_waitcnt lgkmcnt(0)
	v_pk_add_f32 v[30:31], v[32:33], v[36:37]
	ds_bpermute_b32 v33, v174, v31
	ds_bpermute_b32 v32, v174, v30
	v_pk_mul_f32 v[14:15], v[14:15], v[40:41]
	s_waitcnt lgkmcnt(0)
	v_pk_add_f32 v[30:31], v[30:31], v[32:33]
	v_cvt_pk_bf16_f32 v17, v14, v15
	v_add_u32_e32 v14, s17, v44
	ds_bpermute_b32 v33, v175, v31
	ds_bpermute_b32 v32, v175, v30
	v_ashrrev_i32_e32 v15, 31, v14
	v_lshlrev_b64 v[14:15], 11, v[14:15]
	v_lshl_add_u64 v[14:15], s[14:15], 0, v[14:15]
	v_lshl_add_u64 v[14:15], v[14:15], 0, v[18:19]
	global_store_dwordx2 v[14:15], v[16:17], off offset:1024
	s_waitcnt lgkmcnt(0)
	v_pk_add_f32 v[16:17], v[30:31], v[32:33]
	v_add_u32_e32 v14, s17, v25
	v_pk_fma_f32 v[30:31], v[16:17], s[10:11], v[20:21] op_sel_hi:[1,0,0]
	s_nop 0
	v_mul_f32_e32 v15, 0x4b800000, v31
	v_cmp_gt_f32_e32 vcc, s27, v31
	s_nop 1
	v_cndmask_b32_e32 v15, v31, v15, vcc
	v_rsq_f32_e32 v16, v15
	v_ashrrev_i32_e32 v15, 31, v14
	v_lshlrev_b64 v[14:15], 11, v[14:15]
	v_lshl_add_u64 v[14:15], s[14:15], 0, v[14:15]
	v_mul_f32_e32 v17, 0x45800000, v16
	v_cndmask_b32_e32 v16, v16, v17, vcc
	v_pk_mul_f32 v[26:27], v[26:27], v[16:17] op_sel_hi:[1,0]
	v_pk_mul_f32 v[16:17], v[28:29], v[16:17] op_sel_hi:[1,0]
	v_pk_fma_f32 v[26:27], v[2:3], v[26:27], v[6:7]
	v_pk_fma_f32 v[16:17], v[4:5], v[16:17], v[8:9]
	v_mul_f32_e32 v25, 0xbfb8aa3b, v26
	v_exp_f32_e32 v25, v25
	v_mul_f32_e32 v28, 0xbfb8aa3b, v27
	v_exp_f32_e32 v29, v28
	v_lshl_add_u64 v[34:35], v[14:15], 0, v[18:19]
	v_add_f32_e32 v25, 1.0, v25
	v_rcp_f32_e32 v28, v25
	v_add_f32_e32 v25, 1.0, v29
	v_mul_f32_e32 v29, 0xbfb8aa3b, v16
	v_exp_f32_e32 v31, v29
	v_mul_f32_e32 v29, 0xbfb8aa3b, v17
	v_exp_f32_e32 v33, v29
	v_rcp_f32_e32 v29, v25
	v_add_f32_e32 v25, 1.0, v31
	v_rcp_f32_e32 v32, v25
	v_add_f32_e32 v25, 1.0, v33
	v_rcp_f32_e32 v33, v25
	v_pk_mul_f32 v[14:15], v[26:27], v[28:29]
	v_or_b32_e32 v25, 4, v24
	v_cvt_pk_bf16_f32 v36, v14, v15
	v_pk_mul_f32 v[14:15], v[16:17], v[32:33]
	v_lshl_add_u32 v16, v25, 10, v23
	ds_read_b128 v[26:29], v16
	v_cvt_pk_bf16_f32 v37, v14, v15
	v_lshl_add_u32 v14, v42, 10, v23
	ds_read_b128 v[14:17], v14
	v_mul_f32_e32 v33, 0x4b800000, v30
	s_waitcnt lgkmcnt(1)
; #define LAS __attribute__((address_space(3)))
; __device__ __forceinline__ unsigned cvtpk(float lo, float hi) { f32x2_t v = {lo, hi}; bf16x2_t b = __builtin_convertvector(v, bf16x2_t); return __builtin_bit_cast(unsigned, b); }
; __device__ __forceinline__ float wave_sum(float v) { v += __shfl_xor(v, 32); v += __shfl_xor(v, 16); v += __shfl_xor(v, 8); v += __shfl_xor(v, 4); v += __shfl_xor(v, 2); v += __shfl_xor(v, 1); return v; }
; __device__ __forceinline__ float silu_f(float g) { return g * __builtin_amdgcn_rcpf(1.f + __builtin_amdgcn_exp2f(g * -1.4426950408889634f)); }
; __device__ void conv_unit(LAS unsigned char* lds, const bf16_t* __restrict__ Z, bf16_t* __restrict__ MIX, int unit,
;                           const float* __restrict__ ccw, const float* __restrict__ ccb, const float* __restrict__ lng, const float* __restrict__ lnb, const float* __restrict__ scw) {
;     ...
;     { const int wid = tid >> 6, lane = tid & 63; const f32x4 gg = *(const f32x4*)(lng + lane * 4), bb = *(const f32x4*)(lnb + lane * 4);
;       for (int j = 0; j < 8; ++j) { const int tok = wid * 8 + j; const f32x4 y = *(LAS const f32x4*)(ub + tok * 256 + lane * 4);
;           const float mean = wave_sum(y[0] + y[1] + y[2] + y[3]) * (1.f / 256.f); const f32x4 d = y - mean;
;           const float var = wave_sum(d[0] * d[0] + d[1] * d[1] + d[2] * d[2] + d[3] * d[3]) * (1.f / 256.f), rstd = rsqrtf(var + 1e-6f);
;           const f32x4 z = d * rstd * gg + bb; u32x2 w; w.x = cvtpk(silu_f(z[0]), silu_f(z[1])); w.y = cvtpk(silu_f(z[2]), silu_f(z[3]));
;           *(u32x2*)(MIX + (size_t)(t0 + tok) * DM + 512 + lane * 4) = w; } }
	v_add_f32_e32 v31, v26, v27
	v_cmp_gt_f32_e32 vcc, s27, v30
	v_add_f32_e32 v31, v28, v31
	v_add_f32_e32 v31, v29, v31
	v_cndmask_b32_e32 v30, v30, v33, vcc
	s_waitcnt lgkmcnt(0)
	v_add_f32_e32 v33, v14, v15
	v_add_f32_e32 v33, v16, v33
	ds_bpermute_b32 v32, v170, v31
	v_add_f32_e32 v33, v17, v33
	ds_bpermute_b32 v38, v170, v33
	global_store_dwordx2 v[34:35], v[36:37], off offset:1024
	v_rsq_f32_e32 v30, v30
	s_waitcnt lgkmcnt(1)
	v_add_f32_e32 v31, v31, v32
	ds_bpermute_b32 v32, v171, v31
	s_waitcnt lgkmcnt(1)
	v_add_f32_e32 v33, v33, v38
	ds_bpermute_b32 v35, v171, v33
	v_mul_f32_e32 v34, 0x45800000, v30
	v_cndmask_b32_e32 v30, v30, v34, vcc
	s_waitcnt lgkmcnt(1)
	v_add_f32_e32 v31, v31, v32
	ds_bpermute_b32 v32, v172, v31
	s_waitcnt lgkmcnt(1)
	v_add_f32_e32 v33, v33, v35
	ds_bpermute_b32 v34, v172, v33
	s_waitcnt lgkmcnt(1)
	v_add_f32_e32 v31, v31, v32
	ds_bpermute_b32 v32, v173, v31
	s_waitcnt lgkmcnt(1)
	v_add_f32_e32 v33, v33, v34
	ds_bpermute_b32 v34, v173, v33
	v_pk_mul_f32 v[10:11], v[10:11], v[30:31] op_sel_hi:[1,0]
	s_waitcnt lgkmcnt(1)
	v_add_f32_e32 v31, v31, v32
	ds_bpermute_b32 v32, v174, v31
	s_waitcnt lgkmcnt(1)
	v_add_f32_e32 v33, v33, v34
	ds_bpermute_b32 v34, v174, v33
	v_pk_fma_f32 v[10:11], v[2:3], v[10:11], v[6:7]
	s_waitcnt lgkmcnt(1)
	v_add_f32_e32 v31, v31, v32
	ds_bpermute_b32 v32, v175, v31
	s_waitcnt lgkmcnt(1)
	v_add_f32_e32 v36, v33, v34
	ds_bpermute_b32 v37, v175, v36
	v_mul_f32_e32 v35, 0xbfb8aa3b, v10
	v_exp_f32_e32 v43, v35
	s_waitcnt lgkmcnt(1)
	v_add_f32_e32 v31, v31, v32
	v_fmamk_f32 v27, v31, 0xbb800000, v27
	v_fmamk_f32 v26, v31, 0xbb800000, v26
	v_fmamk_f32 v29, v31, 0xbb800000, v29
	v_fmac_f32_e32 v28, 0xbb800000, v31
	s_waitcnt lgkmcnt(0)
	v_add_f32_e32 v31, v36, v37
	v_mul_f32_e32 v35, 0xbfb8aa3b, v11
	v_fmamk_f32 v15, v31, 0xbb800000, v15
	v_fmamk_f32 v14, v31, 0xbb800000, v14
	v_exp_f32_e32 v44, v35
	v_pk_mul_f32 v[34:35], v[26:27], v[26:27]
	v_fmamk_f32 v17, v31, 0xbb800000, v17
	v_fmac_f32_e32 v16, 0xbb800000, v31
	v_pk_mul_f32 v[38:39], v[14:15], v[14:15]
	v_pk_mul_f32 v[32:33], v[28:29], v[28:29]
	v_pk_mul_f32 v[36:37], v[16:17], v[16:17]
	v_mov_b32_e32 v40, v38
	v_mov_b32_e32 v41, v34
	v_mov_b32_e32 v34, v39
	v_pk_add_f32 v[34:35], v[40:41], v[34:35]
	v_mov_b32_e32 v38, v36
	v_mov_b32_e32 v39, v32
	v_pk_add_f32 v[34:35], v[38:39], v[34:35]
	v_mov_b32_e32 v32, v37
	v_pk_add_f32 v[32:33], v[32:33], v[34:35]
	ds_bpermute_b32 v35, v170, v33
	ds_bpermute_b32 v34, v170, v32
	v_add_f32_e32 v31, 1.0, v43
	v_rcp_f32_e32 v36, v31
	v_add_f32_e32 v31, 1.0, v44
	v_rcp_f32_e32 v37, v31
	s_waitcnt lgkmcnt(0)
	v_pk_add_f32 v[32:33], v[32:33], v[34:35]
	ds_bpermute_b32 v35, v171, v33
	ds_bpermute_b32 v34, v171, v32
	v_pk_mul_f32 v[12:13], v[12:13], v[30:31] op_sel_hi:[1,0]
	v_pk_mul_f32 v[10:11], v[10:11], v[36:37]
	v_pk_fma_f32 v[12:13], v[4:5], v[12:13], v[8:9]
	v_cvt_pk_bf16_f32 v10, v10, v11
	s_waitcnt lgkmcnt(0)
	v_pk_add_f32 v[30:31], v[32:33], v[34:35]
	ds_bpermute_b32 v33, v172, v31
	ds_bpermute_b32 v32, v172, v30
	v_mul_f32_e32 v11, 0xbfb8aa3b, v12
	v_exp_f32_e32 v11, v11
	v_mul_f32_e32 v34, 0xbfb8aa3b, v13
	v_exp_f32_e32 v35, v34
	s_waitcnt lgkmcnt(0)
	v_pk_add_f32 v[30:31], v[30:31], v[32:33]
	ds_bpermute_b32 v33, v173, v31
	ds_bpermute_b32 v32, v173, v30
	v_add_f32_e32 v11, 1.0, v11
	v_rcp_f32_e32 v34, v11
	v_add_f32_e32 v11, 1.0, v35
	v_rcp_f32_e32 v35, v11
	s_waitcnt lgkmcnt(0)
	v_pk_add_f32 v[30:31], v[30:31], v[32:33]
	ds_bpermute_b32 v33, v174, v31
	ds_bpermute_b32 v32, v174, v30
	v_pk_mul_f32 v[12:13], v[12:13], v[34:35]
	v_or_b32_e32 v36, 6, v24
	v_cvt_pk_bf16_f32 v11, v12, v13
	v_add_u32_e32 v12, s17, v45
	s_waitcnt lgkmcnt(0)
	v_pk_add_f32 v[30:31], v[30:31], v[32:33]
	ds_bpermute_b32 v33, v175, v31
	ds_bpermute_b32 v32, v175, v30
	v_ashrrev_i32_e32 v13, 31, v12
	v_lshlrev_b64 v[12:13], 11, v[12:13]
	v_lshl_add_u64 v[12:13], s[14:15], 0, v[12:13]
	v_lshl_add_u64 v[12:13], v[12:13], 0, v[18:19]
	global_store_dwordx2 v[12:13], v[10:11], off offset:1024
	s_waitcnt lgkmcnt(0)
	v_pk_add_f32 v[10:11], v[30:31], v[32:33]
	v_or_b32_e32 v37, 7, v22
	v_pk_fma_f32 v[10:11], v[10:11], s[10:11], v[20:21] op_sel_hi:[1,0,0]
	v_lshl_add_u32 v22, v37, 10, v23
	v_mul_f32_e32 v12, 0x4b800000, v11
	v_cmp_gt_f32_e32 vcc, s27, v11
	s_nop 1
	v_cndmask_b32_e32 v11, v11, v12, vcc
	v_rsq_f32_e32 v11, v11
	v_add_u32_e32 v12, s17, v25
	v_ashrrev_i32_e32 v13, 31, v12
	v_lshlrev_b64 v[12:13], 11, v[12:13]
	v_mul_f32_e32 v25, 0x45800000, v11
	v_cndmask_b32_e32 v30, v11, v25, vcc
	v_pk_mul_f32 v[26:27], v[26:27], v[30:31] op_sel_hi:[1,0]
	v_lshl_add_u64 v[12:13], s[14:15], 0, v[12:13]
	v_pk_fma_f32 v[26:27], v[2:3], v[26:27], v[6:7]
	v_lshl_add_u64 v[34:35], v[12:13], 0, v[18:19]
	v_mul_f32_e32 v11, 0xbfb8aa3b, v26
	v_exp_f32_e32 v11, v11
	v_mul_f32_e32 v25, 0xbfb8aa3b, v27
	v_exp_f32_e32 v25, v25
	v_pk_mul_f32 v[12:13], v[28:29], v[30:31] op_sel_hi:[1,0]
	v_add_f32_e32 v11, 1.0, v11
	v_rcp_f32_e32 v32, v11
	v_add_f32_e32 v11, 1.0, v25
	v_pk_fma_f32 v[28:29], v[4:5], v[12:13], v[8:9]
	v_rcp_f32_e32 v33, v11
	v_mul_f32_e32 v11, 0xbfb8aa3b, v28
	v_exp_f32_e32 v11, v11
	v_mul_f32_e32 v25, 0xbfb8aa3b, v29
	v_exp_f32_e32 v25, v25
	v_cmp_gt_f32_e32 vcc, s27, v10
	v_add_f32_e32 v11, 1.0, v11
	v_rcp_f32_e32 v30, v11
	v_add_f32_e32 v11, 1.0, v25
	v_rcp_f32_e32 v31, v11
	v_mul_f32_e32 v11, 0x4b800000, v10
	v_pk_mul_f32 v[12:13], v[26:27], v[32:33]
	v_cndmask_b32_e32 v25, v10, v11, vcc
	v_lshl_add_u32 v10, v36, 10, v23
	v_cvt_pk_bf16_f32 v26, v12, v13
	ds_read_b128 v[10:13], v10
	v_rsq_f32_e32 v32, v25
	ds_read_b128 v[22:25], v22
	v_pk_mul_f32 v[28:29], v[28:29], v[30:31]
	s_waitcnt lgkmcnt(1)
; #define LAS __attribute__((address_space(3)))
; __device__ __forceinline__ unsigned cvtpk(float lo, float hi) { f32x2_t v = {lo, hi}; bf16x2_t b = __builtin_convertvector(v, bf16x2_t); return __builtin_bit_cast(unsigned, b); }
; __device__ __forceinline__ float wave_sum(float v) { v += __shfl_xor(v, 32); v += __shfl_xor(v, 16); v += __shfl_xor(v, 8); v += __shfl_xor(v, 4); v += __shfl_xor(v, 2); v += __shfl_xor(v, 1); return v; }
; __device__ void conv_unit(LAS unsigned char* lds, const bf16_t* __restrict__ Z, bf16_t* __restrict__ MIX, int unit,
;                           const float* __restrict__ ccw, const float* __restrict__ ccb, const float* __restrict__ lng, const float* __restrict__ lnb, const float* __restrict__ scw) {
;     ...
;     { const int wid = tid >> 6, lane = tid & 63; const f32x4 gg = *(const f32x4*)(lng + lane * 4), bb = *(const f32x4*)(lnb + lane * 4);
;       for (int j = 0; j < 8; ++j) { const int tok = wid * 8 + j; const f32x4 y = *(LAS const f32x4*)(ub + tok * 256 + lane * 4);
;           const float mean = wave_sum(y[0] + y[1] + y[2] + y[3]) * (1.f / 256.f); const f32x4 d = y - mean;
;           const float var = wave_sum(d[0] * d[0] + d[1] * d[1] + d[2] * d[2] + d[3] * d[3]) * (1.f / 256.f), rstd = rsqrtf(var + 1e-6f);
;           const f32x4 z = d * rstd * gg + bb; u32x2 w; w.x = cvtpk(silu_f(z[0]), silu_f(z[1])); w.y = cvtpk(silu_f(z[2]), silu_f(z[3]));
;           *(u32x2*)(MIX + (size_t)(t0 + tok) * DM + 512 + lane * 4) = w; } }
;     ...
;     for (int i = 0; i < 4; ++i) { const int id = tid + 512 * i, tok = id >> 5, c8 = (id & 31) * 8, tp = tpos0 + tok; const bf16_t* zr = Z + (size_t)(t0 + tok) * DIN + 2048 + c8;
;         u32x4 gcv[3], hsv[3];
; #pragma unroll
;         for (int k = 0; k < 3; ++k) { int back = 2 - k; back = (t0 + tok - back < 0) ? 0 : back; const bf16_t* zk = zr - (size_t)back * DIN; gcv[k] = *(const u32x4*)(zk + 256); hsv[k] = *(const u32x4*)(zk + 512); }
;         const u32x4 gb = *(const u32x4*)zr;
;         float y[8];
; #pragma unroll
;         for (int e = 0; e < 8; ++e) y[e] = 0.f;
; #pragma unroll
;         for (int k = 0; k < 3; ++k) { const u32x4 gc = gcv[k], hs = hsv[k]; const float on = (tp - 2 + k >= 0) ? 1.f : 0.f;
;                 const f32x4 w0 = *(const f32x4*)(scw + k * 256 + c8) * on, w1 = *(const f32x4*)(scw + k * 256 + c8 + 4) * on;
	v_add_f32_e32 v27, v10, v11
	v_add_f32_e32 v27, v12, v27
	v_add_f32_e32 v33, v13, v27
	ds_bpermute_b32 v38, v170, v33
	v_cvt_pk_bf16_f32 v27, v28, v29
	s_waitcnt lgkmcnt(1)
	v_add_f32_e32 v29, v22, v23
	v_add_f32_e32 v29, v24, v29
	global_store_dwordx2 v[34:35], v[26:27], off offset:1024
	s_waitcnt lgkmcnt(0)
	v_add_f32_e32 v27, v33, v38
	v_add_f32_e32 v29, v25, v29
	ds_bpermute_b32 v28, v171, v27
	ds_bpermute_b32 v30, v170, v29
	v_mul_f32_e32 v26, 0x45800000, v32
	v_cndmask_b32_e32 v26, v32, v26, vcc
	s_waitcnt lgkmcnt(1)
	v_add_f32_e32 v27, v27, v28
	s_waitcnt lgkmcnt(0)
	v_add_f32_e32 v29, v29, v30
	ds_bpermute_b32 v28, v172, v27
	ds_bpermute_b32 v30, v171, v29
	v_pk_mul_f32 v[14:15], v[14:15], v[26:27] op_sel_hi:[1,0]
	v_pk_mul_f32 v[16:17], v[16:17], v[26:27] op_sel_hi:[1,0]
	v_pk_fma_f32 v[14:15], v[2:3], v[14:15], v[6:7]
	s_waitcnt lgkmcnt(1)
	v_add_f32_e32 v26, v27, v28
	s_waitcnt lgkmcnt(0)
	v_add_f32_e32 v28, v29, v30
	ds_bpermute_b32 v29, v172, v28
	ds_bpermute_b32 v27, v173, v26
	v_mul_f32_e32 v30, 0xbfb8aa3b, v14
	v_exp_f32_e32 v38, v30
	v_mul_f32_e32 v30, 0xbfb8aa3b, v15
	s_waitcnt lgkmcnt(1)
	v_add_f32_e32 v28, v28, v29
	ds_bpermute_b32 v29, v173, v28
	s_waitcnt lgkmcnt(1)
	v_add_f32_e32 v26, v26, v27
	ds_bpermute_b32 v27, v174, v26
	v_exp_f32_e32 v39, v30
	v_pk_fma_f32 v[16:17], v[4:5], v[16:17], v[8:9]
	s_waitcnt lgkmcnt(1)
	v_add_f32_e32 v28, v28, v29
	ds_bpermute_b32 v29, v174, v28
	s_waitcnt lgkmcnt(1)
	v_add_f32_e32 v26, v26, v27
	ds_bpermute_b32 v27, v175, v26
	s_waitcnt lgkmcnt(1)
	v_add_f32_e32 v30, v28, v29
	ds_bpermute_b32 v31, v175, v30
	s_waitcnt lgkmcnt(1)
	v_add_f32_e32 v26, v26, v27
	v_fmamk_f32 v11, v26, 0xbb800000, v11
	v_fmamk_f32 v10, v26, 0xbb800000, v10
	v_fmamk_f32 v13, v26, 0xbb800000, v13
	s_waitcnt lgkmcnt(0)
	v_add_f32_e32 v30, v30, v31
	v_fmamk_f32 v23, v30, 0xbb800000, v23
	v_fmamk_f32 v22, v30, 0xbb800000, v22
	v_fmac_f32_e32 v12, 0xbb800000, v26
	v_pk_mul_f32 v[28:29], v[10:11], v[10:11]
	v_fmamk_f32 v25, v30, 0xbb800000, v25
	v_fmac_f32_e32 v24, 0xbb800000, v30
	v_pk_mul_f32 v[32:33], v[22:23], v[22:23]
	v_pk_mul_f32 v[26:27], v[12:13], v[12:13]
	v_pk_mul_f32 v[30:31], v[24:25], v[24:25]
	v_mov_b32_e32 v34, v32
	v_mov_b32_e32 v35, v28
	v_mov_b32_e32 v28, v33
	v_pk_add_f32 v[28:29], v[34:35], v[28:29]
	v_mov_b32_e32 v32, v30
	v_mov_b32_e32 v33, v26
	v_pk_add_f32 v[28:29], v[32:33], v[28:29]
	v_mov_b32_e32 v26, v31
	v_pk_add_f32 v[26:27], v[26:27], v[28:29]
	ds_bpermute_b32 v29, v170, v27
	ds_bpermute_b32 v28, v170, v26
	v_mul_f32_e32 v32, 0xbfb8aa3b, v16
	v_mul_f32_e32 v33, 0xbfb8aa3b, v17
	v_exp_f32_e32 v32, v32
	v_exp_f32_e32 v33, v33
	s_waitcnt lgkmcnt(0)
	v_pk_add_f32 v[26:27], v[26:27], v[28:29]
	ds_bpermute_b32 v29, v171, v27
	ds_bpermute_b32 v28, v171, v26
	v_add_f32_e32 v30, 1.0, v38
	v_add_f32_e32 v31, 1.0, v39
	v_add_f32_e32 v32, 1.0, v32
	v_add_f32_e32 v33, 1.0, v33
	s_waitcnt lgkmcnt(0)
	v_pk_add_f32 v[26:27], v[26:27], v[28:29]
	ds_bpermute_b32 v29, v172, v27
	ds_bpermute_b32 v28, v172, v26
	v_rcp_f32_e32 v30, v30
	v_rcp_f32_e32 v31, v31
	v_rcp_f32_e32 v32, v32
	v_rcp_f32_e32 v33, v33
	s_waitcnt lgkmcnt(0)
	v_pk_add_f32 v[26:27], v[26:27], v[28:29]
	ds_bpermute_b32 v29, v173, v27
	ds_bpermute_b32 v28, v173, v26
	v_pk_mul_f32 v[14:15], v[14:15], v[30:31]
	v_pk_mul_f32 v[16:17], v[16:17], v[32:33]
	v_cvt_pk_bf16_f32 v14, v14, v15
	v_cvt_pk_bf16_f32 v15, v16, v17
	s_waitcnt lgkmcnt(0)
	v_pk_add_f32 v[16:17], v[26:27], v[28:29]
	ds_bpermute_b32 v27, v174, v17
	ds_bpermute_b32 v26, v174, v16
	v_add_u32_e32 v28, s17, v42
	v_ashrrev_i32_e32 v29, 31, v28
	v_lshlrev_b64 v[28:29], 11, v[28:29]
	v_lshl_add_u64 v[28:29], s[14:15], 0, v[28:29]
	s_waitcnt lgkmcnt(0)
	v_pk_add_f32 v[16:17], v[16:17], v[26:27]
	ds_bpermute_b32 v27, v175, v17
	ds_bpermute_b32 v26, v175, v16
	v_lshl_add_u64 v[28:29], v[28:29], 0, v[18:19]
	global_store_dwordx2 v[28:29], v[14:15], off offset:1024
	v_add_u32_e32 v14, s17, v36
	v_ashrrev_i32_e32 v15, 31, v14
	s_waitcnt lgkmcnt(0)
	v_pk_add_f32 v[16:17], v[16:17], v[26:27]
	v_lshlrev_b64 v[14:15], 11, v[14:15]
	v_pk_fma_f32 v[16:17], v[16:17], s[10:11], v[20:21] op_sel_hi:[1,0,0]
	v_lshl_add_u64 v[14:15], s[14:15], 0, v[14:15]
	v_mul_f32_e32 v20, 0x4b800000, v17
	v_cmp_gt_f32_e32 vcc, s27, v17
	v_lshl_add_u64 v[14:15], v[14:15], 0, v[18:19]
	s_mov_b32 s10, 0
	v_cndmask_b32_e32 v17, v17, v20, vcc
	v_rsq_f32_e32 v17, v17
	s_nop 0
	v_mul_f32_e32 v20, 0x45800000, v17
	v_cndmask_b32_e32 v20, v17, v20, vcc
	v_pk_mul_f32 v[10:11], v[10:11], v[20:21] op_sel_hi:[1,0]
	v_pk_mul_f32 v[12:13], v[12:13], v[20:21] op_sel_hi:[1,0]
	v_pk_fma_f32 v[10:11], v[2:3], v[10:11], v[6:7]
	v_pk_fma_f32 v[12:13], v[4:5], v[12:13], v[8:9]
	v_mul_f32_e32 v17, 0xbfb8aa3b, v10
	v_exp_f32_e32 v17, v17
	v_mul_f32_e32 v20, 0xbfb8aa3b, v11
	v_exp_f32_e32 v21, v20
	v_mul_f32_e32 v26, 0xbfb8aa3b, v13
	v_add_f32_e32 v17, 1.0, v17
	v_rcp_f32_e32 v20, v17
	v_add_f32_e32 v17, 1.0, v21
	v_rcp_f32_e32 v21, v17
	v_mul_f32_e32 v17, 0xbfb8aa3b, v12
	v_exp_f32_e32 v17, v17
	v_exp_f32_e32 v26, v26
	v_pk_mul_f32 v[10:11], v[10:11], v[20:21]
	v_cmp_gt_f32_e32 vcc, s27, v16
	v_add_f32_e32 v17, 1.0, v17
	v_rcp_f32_e32 v20, v17
	v_add_f32_e32 v17, 1.0, v26
	v_rcp_f32_e32 v21, v17
	v_mul_f32_e32 v17, 0x4b800000, v16
	v_cndmask_b32_e32 v16, v16, v17, vcc
	v_rsq_f32_e32 v16, v16
	v_pk_mul_f32 v[12:13], v[12:13], v[20:21]
	v_cvt_pk_bf16_f32 v10, v10, v11
	v_cvt_pk_bf16_f32 v11, v12, v13
	v_mul_f32_e32 v12, 0x45800000, v16
	v_cndmask_b32_e32 v12, v16, v12, vcc
	v_pk_mul_f32 v[16:17], v[22:23], v[12:13] op_sel_hi:[1,0]
	v_pk_mul_f32 v[12:13], v[24:25], v[12:13] op_sel_hi:[1,0]
	v_pk_fma_f32 v[2:3], v[2:3], v[16:17], v[6:7]
	v_pk_fma_f32 v[4:5], v[4:5], v[12:13], v[8:9]
	v_mul_f32_e32 v6, 0xbfb8aa3b, v2
	v_mul_f32_e32 v7, 0xbfb8aa3b, v3
	v_mul_f32_e32 v8, 0xbfb8aa3b, v4
	v_mul_f32_e32 v9, 0xbfb8aa3b, v5
	v_exp_f32_e32 v6, v6
	v_exp_f32_e32 v7, v7
	v_exp_f32_e32 v8, v8
	v_exp_f32_e32 v9, v9
	v_add_f32_e32 v6, 1.0, v6
	v_add_f32_e32 v7, 1.0, v7
	v_add_f32_e32 v8, 1.0, v8
	v_add_f32_e32 v9, 1.0, v9
	v_rcp_f32_e32 v6, v6
	v_rcp_f32_e32 v7, v7
	v_rcp_f32_e32 v8, v8
	v_rcp_f32_e32 v9, v9
	global_store_dwordx2 v[14:15], v[10:11], off offset:1024
	v_pk_mul_f32 v[2:3], v[2:3], v[6:7]
	v_lshlrev_b32_e32 v22, 2, v101
	v_pk_mul_f32 v[4:5], v[4:5], v[8:9]
	v_cvt_pk_bf16_f32 v2, v2, v3
	v_cvt_pk_bf16_f32 v3, v4, v5
	v_add_u32_e32 v4, s17, v37
	v_ashrrev_i32_e32 v5, 31, v4
	v_lshlrev_b64 v[4:5], 11, v[4:5]
	v_lshl_add_u64 v[4:5], s[14:15], 0, v[4:5]
	v_lshl_add_u64 v[4:5], v[4:5], 0, v[18:19]
	global_store_dwordx2 v[4:5], v[2:3], off offset:1024
	global_load_dwordx4 v[2:5], v22, s[40:41] offset:16
	s_nop 0
	global_load_dwordx4 v[6:9], v22, s[40:41]
	global_load_dwordx4 v[10:13], v22, s[40:41] offset:1040
	global_load_dwordx4 v[14:17], v22, s[40:41] offset:1024
	global_load_dwordx4 v[18:21], v22, s[40:41] offset:2064
	s_nop 0
	global_load_dwordx4 v[22:25], v22, s[40:41] offset:2048
	v_lshl_add_u64 v[26:27], s[14:15], 0, v[0:1]
